# v13 + first-barrier XCD census: the 16 sc1 counter loads issued together and waited once instead of one vmcnt(0) per load
# baseline (speedup 1.0000x reference)
; __device__ __forceinline__ unsigned xb_ld(unsigned* p)              { return __hip_atomic_load(p, __ATOMIC_RELAXED, __HIP_MEMORY_SCOPE_AGENT); }
; __device__ __forceinline__ void xcd_barrier_complete(unsigned* bar, unsigned x, unsigned& nloc, unsigned& nx) {
;     ...
;     for (;;) {
;         sum = 0u; cnt = 0u; mine = 0u;
; #pragma unroll
;         for (unsigned j = 0; j < 16; ++j) { const unsigned c = xb_ld(&bar[XB_XCNT(j)]); sum += c; cnt += (c > 0u) ? 1u : 0u; mine = (j == x) ? c : mine; }
;         if (sum == G) break;
;         __builtin_amdgcn_s_sleep(1);
;         if ((++sp & 255u) == 0u) { if (xb_ld(&bar[XB_TMO])) break; if (sp > XB_SPIN_CAP) { atomicAdd(&bar[XB_TMO], 1u); break; } }
;     }
.LBB0_1111:
	v_readlane_b32 s2, v252, 29
	v_readlane_b32 s3, v252, 30
	s_mov_b64 s[6:7], -1
	s_nop 3
	global_load_dword v0, v185, s[2:3] sc1
	v_readlane_b32 s2, v252, 31
	v_readlane_b32 s3, v252, 32
	s_nop 4
	global_load_dword v1, v185, s[2:3] sc1
	v_readlane_b32 s2, v252, 33
	v_readlane_b32 s3, v252, 34
	s_nop 4
	global_load_dword v2, v185, s[2:3] sc1
	v_readlane_b32 s2, v252, 35
	v_readlane_b32 s3, v252, 36
	s_nop 4
	global_load_dword v3, v185, s[2:3] sc1
	v_readlane_b32 s2, v252, 37
	v_readlane_b32 s3, v252, 38
	s_nop 4
	global_load_dword v4, v185, s[2:3] sc1
	v_readlane_b32 s2, v252, 39
	v_readlane_b32 s3, v252, 40
	s_nop 4
	global_load_dword v5, v185, s[2:3] sc1
	v_readlane_b32 s2, v252, 41
	v_readlane_b32 s3, v252, 42
	s_nop 4
	global_load_dword v6, v185, s[2:3] sc1
	v_readlane_b32 s2, v252, 43
	v_readlane_b32 s3, v252, 44
	s_nop 4
	global_load_dword v7, v185, s[2:3] sc1
	v_readlane_b32 s2, v252, 45
	v_readlane_b32 s3, v252, 46
	s_nop 4
	global_load_dword v8, v185, s[2:3] sc1
	v_readlane_b32 s2, v252, 47
	v_readlane_b32 s3, v252, 48
	s_nop 4
	global_load_dword v9, v185, s[2:3] sc1
	v_readlane_b32 s2, v252, 49
	v_readlane_b32 s3, v252, 50
	s_nop 4
	global_load_dword v10, v185, s[2:3] sc1
	v_readlane_b32 s2, v252, 51
	v_readlane_b32 s3, v252, 52
	s_nop 4
	global_load_dword v11, v185, s[2:3] sc1
	v_readlane_b32 s2, v252, 53
	v_readlane_b32 s3, v252, 54
	s_nop 4
	global_load_dword v12, v185, s[2:3] sc1
	v_readlane_b32 s2, v252, 55
	v_readlane_b32 s3, v252, 56
	s_nop 4
	global_load_dword v13, v185, s[2:3] sc1
	v_readlane_b32 s2, v252, 57
	v_readlane_b32 s3, v252, 58
	s_nop 4
	global_load_dword v14, v185, s[2:3] sc1
	v_readlane_b32 s2, v252, 59
	v_readlane_b32 s3, v252, 60
	s_nop 4
	global_load_dword v15, v185, s[2:3] sc1
	s_mov_b64 s[2:3], -1
	s_waitcnt vmcnt(0)
	v_add_u32_e32 v16, v1, v0
	v_add_u32_e32 v16, v16, v2
	v_add_u32_e32 v16, v16, v3
	v_add_u32_e32 v16, v16, v4
	v_add_u32_e32 v16, v16, v5
	v_add_u32_e32 v16, v16, v6
	v_add_u32_e32 v16, v16, v7
	v_add_u32_e32 v16, v16, v8
	v_add_u32_e32 v16, v16, v9
	v_add_u32_e32 v16, v16, v10
	v_add_u32_e32 v16, v16, v11
	v_add_u32_e32 v16, v16, v12
	v_add_u32_e32 v16, v16, v13
	v_add_u32_e32 v16, v16, v14
	v_add_u32_e32 v16, v16, v15
	v_cmp_eq_u32_e32 vcc, s8, v16
	s_cbranch_vccnz .LBB0_1110
	s_and_b32 s2, s9, 0xff
	s_cmp_eq_u32 s2, 0
	s_mov_b64 s[2:3], -1
	s_mov_b64 s[4:5], -1
	s_sleep 1
	s_cbranch_scc1 .LBB0_1115
	s_and_b64 vcc, exec, s[4:5]
	s_cbranch_vccz .LBB0_1110
